# seam 0: adaLN outputs stored write-through (sc1), per-WG L2 write-back dropped at seam 0 (weights flushed by seam-1 XCD leaders)
# baseline (speedup 1.0000x reference)
; #define LAS __attribute__((address_space(3)))
; __device__ __forceinline__ void p0_phase(LAS unsigned char* lds, const float* c, const float* w_ada, const float* b_ada, const float* w_in, const float* w_out,
;                                          float* mod, bf16* win_t, bf16* wout_t, int tid, int wid, int lane) {
;     ...
;         for (int k = 0; k < 128; k += 4) {
;             const float w0 = wp[(size_t)k * 3072], w1 = wp[(size_t)(k + 1) * 3072], w2 = wp[(size_t)(k + 2) * 3072], w3 = wp[(size_t)(k + 3) * 3072];
; #pragma unroll
;             for (int b = 0; b < 32; ++b) { const f32x4 cv = *(const LAS f32x4*)(cs + b * 1024 + kbase + k); acc[b] += cv[0] * w0 + cv[1] * w1 + cv[2] * w2 + cv[3] * w3; }
;         }
.LBB0_21:
	v_mov_b32_e32 v94, s35
	s_add_i32 s36, s35, 0x10000
	v_mov_b32_e32 v95, s36
	v_add_co_u32_e32 v92, vcc, s24, v16
	s_nop 1
	v_addc_co_u32_e32 v93, vcc, -1, v17, vcc
	global_load_dword v84, v[92:93], off
	v_lshl_add_u64 v[92:93], v[92:93], 0, s[48:49]
	global_load_dword v85, v[92:93], off
	v_lshl_add_u64 v[92:93], v[92:93], 0, s[48:49]
	global_load_dword v86, v[92:93], off
	v_lshl_add_u64 v[92:93], v[92:93], 0, s[48:49]
	global_load_dword v87, v[92:93], off
	v_lshl_add_u64 v[92:93], v[92:93], 0, s[48:49]
	global_load_dword v88, v[92:93], off
	v_lshl_add_u64 v[92:93], v[92:93], 0, s[48:49]
	global_load_dword v89, v[92:93], off
	v_lshl_add_u64 v[92:93], v[92:93], 0, s[48:49]
	global_load_dword v90, v[92:93], off
	v_lshl_add_u64 v[92:93], v[92:93], 0, s[48:49]
	global_load_dword v91, v[92:93], off
	v_lshl_add_u64 v[16:17], v[16:17], 0, s[14:15]
	s_waitcnt vmcnt(8)
	ds_read_b128 v[96:99], v94 offset:0
	ds_read_b128 v[100:103], v94 offset:16
	ds_read_b128 v[104:107], v94 offset:4096
	ds_read_b128 v[108:111], v94 offset:4112
	ds_read_b128 v[112:115], v94 offset:8192
	ds_read_b128 v[116:119], v94 offset:8208
	ds_read_b128 v[120:123], v94 offset:12288
	ds_read_b128 v[124:127], v94 offset:12304
	s_waitcnt lgkmcnt(6)
	v_fmac_f32_e32 v18, v76, v96
	v_fmac_f32_e32 v18, v77, v97
	v_fmac_f32_e32 v18, v78, v98
	v_fmac_f32_e32 v18, v79, v99
	v_fmac_f32_e32 v18, v80, v100
	v_fmac_f32_e32 v18, v81, v101
	v_fmac_f32_e32 v18, v82, v102
	v_fmac_f32_e32 v18, v83, v103
	ds_read_b128 v[96:99], v94 offset:16384
	ds_read_b128 v[100:103], v94 offset:16400
	s_waitcnt lgkmcnt(6)
	v_fmac_f32_e32 v19, v76, v104
	v_fmac_f32_e32 v19, v77, v105
	v_fmac_f32_e32 v19, v78, v106
	v_fmac_f32_e32 v19, v79, v107
	v_fmac_f32_e32 v19, v80, v108
	v_fmac_f32_e32 v19, v81, v109
	v_fmac_f32_e32 v19, v82, v110
	v_fmac_f32_e32 v19, v83, v111
	ds_read_b128 v[104:107], v94 offset:20480
	ds_read_b128 v[108:111], v94 offset:20496
	s_waitcnt lgkmcnt(6)
	v_fmac_f32_e32 v20, v76, v112
	v_fmac_f32_e32 v20, v77, v113
	v_fmac_f32_e32 v20, v78, v114
	v_fmac_f32_e32 v20, v79, v115
	v_fmac_f32_e32 v20, v80, v116
	v_fmac_f32_e32 v20, v81, v117
	v_fmac_f32_e32 v20, v82, v118
	v_fmac_f32_e32 v20, v83, v119
	ds_read_b128 v[112:115], v94 offset:24576
	ds_read_b128 v[116:119], v94 offset:24592
	s_waitcnt lgkmcnt(6)
	v_fmac_f32_e32 v21, v76, v120
	v_fmac_f32_e32 v21, v77, v121
	v_fmac_f32_e32 v21, v78, v122
	v_fmac_f32_e32 v21, v79, v123
	v_fmac_f32_e32 v21, v80, v124
	v_fmac_f32_e32 v21, v81, v125
	v_fmac_f32_e32 v21, v82, v126
	v_fmac_f32_e32 v21, v83, v127
	ds_read_b128 v[120:123], v94 offset:28672
	ds_read_b128 v[124:127], v94 offset:28688
	s_waitcnt lgkmcnt(6)
	v_fmac_f32_e32 v22, v76, v96
	v_fmac_f32_e32 v22, v77, v97
	v_fmac_f32_e32 v22, v78, v98
	v_fmac_f32_e32 v22, v79, v99
	v_fmac_f32_e32 v22, v80, v100
	v_fmac_f32_e32 v22, v81, v101
	v_fmac_f32_e32 v22, v82, v102
	v_fmac_f32_e32 v22, v83, v103
	ds_read_b128 v[96:99], v94 offset:32768
	ds_read_b128 v[100:103], v94 offset:32784
	s_waitcnt lgkmcnt(6)
	v_fmac_f32_e32 v23, v76, v104
	v_fmac_f32_e32 v23, v77, v105
	v_fmac_f32_e32 v23, v78, v106
	v_fmac_f32_e32 v23, v79, v107
	v_fmac_f32_e32 v23, v80, v108
	v_fmac_f32_e32 v23, v81, v109
	v_fmac_f32_e32 v23, v82, v110
	v_fmac_f32_e32 v23, v83, v111
	ds_read_b128 v[104:107], v94 offset:36864
	ds_read_b128 v[108:111], v94 offset:36880
	s_waitcnt lgkmcnt(6)
	v_fmac_f32_e32 v24, v76, v112
	v_fmac_f32_e32 v24, v77, v113
	v_fmac_f32_e32 v24, v78, v114
	v_fmac_f32_e32 v24, v79, v115
	v_fmac_f32_e32 v24, v80, v116
	v_fmac_f32_e32 v24, v81, v117
	v_fmac_f32_e32 v24, v82, v118
	v_fmac_f32_e32 v24, v83, v119
	ds_read_b128 v[112:115], v94 offset:40960
	ds_read_b128 v[116:119], v94 offset:40976
	s_waitcnt lgkmcnt(6)
	v_fmac_f32_e32 v25, v76, v120
	v_fmac_f32_e32 v25, v77, v121
	v_fmac_f32_e32 v25, v78, v122
	v_fmac_f32_e32 v25, v79, v123
	v_fmac_f32_e32 v25, v80, v124
	v_fmac_f32_e32 v25, v81, v125
	v_fmac_f32_e32 v25, v82, v126
	v_fmac_f32_e32 v25, v83, v127
	ds_read_b128 v[120:123], v94 offset:45056
	ds_read_b128 v[124:127], v94 offset:45072
	s_waitcnt lgkmcnt(6)
	v_fmac_f32_e32 v26, v76, v96
	v_fmac_f32_e32 v26, v77, v97
	v_fmac_f32_e32 v26, v78, v98
	v_fmac_f32_e32 v26, v79, v99
	v_fmac_f32_e32 v26, v80, v100
	v_fmac_f32_e32 v26, v81, v101
	v_fmac_f32_e32 v26, v82, v102
	v_fmac_f32_e32 v26, v83, v103
	ds_read_b128 v[96:99], v94 offset:49152
	ds_read_b128 v[100:103], v94 offset:49168
	s_waitcnt lgkmcnt(6)
	v_fmac_f32_e32 v27, v76, v104
	v_fmac_f32_e32 v27, v77, v105
	v_fmac_f32_e32 v27, v78, v106
	v_fmac_f32_e32 v27, v79, v107
	v_fmac_f32_e32 v27, v80, v108
	v_fmac_f32_e32 v27, v81, v109
	v_fmac_f32_e32 v27, v82, v110
	v_fmac_f32_e32 v27, v83, v111
	ds_read_b128 v[104:107], v94 offset:53248
	ds_read_b128 v[108:111], v94 offset:53264
	s_waitcnt lgkmcnt(6)
	v_fmac_f32_e32 v28, v76, v112
	v_fmac_f32_e32 v28, v77, v113
	v_fmac_f32_e32 v28, v78, v114
	v_fmac_f32_e32 v28, v79, v115
	v_fmac_f32_e32 v28, v80, v116
	v_fmac_f32_e32 v28, v81, v117
	v_fmac_f32_e32 v28, v82, v118
	v_fmac_f32_e32 v28, v83, v119
	ds_read_b128 v[112:115], v94 offset:57344
	ds_read_b128 v[116:119], v94 offset:57360
	s_waitcnt lgkmcnt(6)
	v_fmac_f32_e32 v29, v76, v120
	v_fmac_f32_e32 v29, v77, v121
	v_fmac_f32_e32 v29, v78, v122
	v_fmac_f32_e32 v29, v79, v123
	v_fmac_f32_e32 v29, v80, v124
	v_fmac_f32_e32 v29, v81, v125
	v_fmac_f32_e32 v29, v82, v126
	v_fmac_f32_e32 v29, v83, v127
	ds_read_b128 v[120:123], v94 offset:61440
	ds_read_b128 v[124:127], v94 offset:61456
	s_waitcnt lgkmcnt(6)
; #define LAS __attribute__((address_space(3)))
; __device__ __forceinline__ void p0_phase(LAS unsigned char* lds, const float* c, const float* w_ada, const float* b_ada, const float* w_in, const float* w_out,
;                                          float* mod, bf16* win_t, bf16* wout_t, int tid, int wid, int lane) {
;     ...
; #pragma unroll 2
;         for (int k = 0; k < 128; k += 4) {
;             const float w0 = wp[(size_t)k * 3072], w1 = wp[(size_t)(k + 1) * 3072], w2 = wp[(size_t)(k + 2) * 3072], w3 = wp[(size_t)(k + 3) * 3072];
; #pragma unroll
;             for (int b = 0; b < 32; ++b) { const f32x4 cv = *(const LAS f32x4*)(cs + b * 1024 + kbase + k); acc[b] += cv[0] * w0 + cv[1] * w1 + cv[2] * w2 + cv[3] * w3; }
;         }
	v_fmac_f32_e32 v30, v76, v96
	v_fmac_f32_e32 v30, v77, v97
	v_fmac_f32_e32 v30, v78, v98
	v_fmac_f32_e32 v30, v79, v99
	v_fmac_f32_e32 v30, v80, v100
	v_fmac_f32_e32 v30, v81, v101
	v_fmac_f32_e32 v30, v82, v102
	v_fmac_f32_e32 v30, v83, v103
	ds_read_b128 v[96:99], v95 offset:0
	ds_read_b128 v[100:103], v95 offset:16
	s_waitcnt lgkmcnt(6)
	v_fmac_f32_e32 v31, v76, v104
	v_fmac_f32_e32 v31, v77, v105
	v_fmac_f32_e32 v31, v78, v106
	v_fmac_f32_e32 v31, v79, v107
	v_fmac_f32_e32 v31, v80, v108
	v_fmac_f32_e32 v31, v81, v109
	v_fmac_f32_e32 v31, v82, v110
	v_fmac_f32_e32 v31, v83, v111
	ds_read_b128 v[104:107], v95 offset:4096
	ds_read_b128 v[108:111], v95 offset:4112
	s_waitcnt lgkmcnt(6)
	v_fmac_f32_e32 v32, v76, v112
	v_fmac_f32_e32 v32, v77, v113
	v_fmac_f32_e32 v32, v78, v114
	v_fmac_f32_e32 v32, v79, v115
	v_fmac_f32_e32 v32, v80, v116
	v_fmac_f32_e32 v32, v81, v117
	v_fmac_f32_e32 v32, v82, v118
	v_fmac_f32_e32 v32, v83, v119
	ds_read_b128 v[112:115], v95 offset:8192
	ds_read_b128 v[116:119], v95 offset:8208
	s_waitcnt lgkmcnt(6)
	v_fmac_f32_e32 v33, v76, v120
	v_fmac_f32_e32 v33, v77, v121
	v_fmac_f32_e32 v33, v78, v122
	v_fmac_f32_e32 v33, v79, v123
	v_fmac_f32_e32 v33, v80, v124
	v_fmac_f32_e32 v33, v81, v125
	v_fmac_f32_e32 v33, v82, v126
	v_fmac_f32_e32 v33, v83, v127
	ds_read_b128 v[120:123], v95 offset:12288
	ds_read_b128 v[124:127], v95 offset:12304
	s_waitcnt lgkmcnt(6)
	v_fmac_f32_e32 v52, v76, v96
	v_fmac_f32_e32 v52, v77, v97
	v_fmac_f32_e32 v52, v78, v98
	v_fmac_f32_e32 v52, v79, v99
	v_fmac_f32_e32 v52, v80, v100
	v_fmac_f32_e32 v52, v81, v101
	v_fmac_f32_e32 v52, v82, v102
	v_fmac_f32_e32 v52, v83, v103
	ds_read_b128 v[96:99], v95 offset:16384
	ds_read_b128 v[100:103], v95 offset:16400
	s_waitcnt lgkmcnt(6)
	v_fmac_f32_e32 v53, v76, v104
	v_fmac_f32_e32 v53, v77, v105
	v_fmac_f32_e32 v53, v78, v106
	v_fmac_f32_e32 v53, v79, v107
	v_fmac_f32_e32 v53, v80, v108
	v_fmac_f32_e32 v53, v81, v109
	v_fmac_f32_e32 v53, v82, v110
	v_fmac_f32_e32 v53, v83, v111
	ds_read_b128 v[104:107], v95 offset:20480
	ds_read_b128 v[108:111], v95 offset:20496
	s_waitcnt lgkmcnt(6)
	v_fmac_f32_e32 v54, v76, v112
	v_fmac_f32_e32 v54, v77, v113
	v_fmac_f32_e32 v54, v78, v114
	v_fmac_f32_e32 v54, v79, v115
	v_fmac_f32_e32 v54, v80, v116
	v_fmac_f32_e32 v54, v81, v117
	v_fmac_f32_e32 v54, v82, v118
	v_fmac_f32_e32 v54, v83, v119
	ds_read_b128 v[112:115], v95 offset:24576
	ds_read_b128 v[116:119], v95 offset:24592
	s_waitcnt lgkmcnt(6)
	v_fmac_f32_e32 v55, v76, v120
	v_fmac_f32_e32 v55, v77, v121
	v_fmac_f32_e32 v55, v78, v122
	v_fmac_f32_e32 v55, v79, v123
	v_fmac_f32_e32 v55, v80, v124
	v_fmac_f32_e32 v55, v81, v125
	v_fmac_f32_e32 v55, v82, v126
	v_fmac_f32_e32 v55, v83, v127
	ds_read_b128 v[120:123], v95 offset:28672
	ds_read_b128 v[124:127], v95 offset:28688
	s_waitcnt lgkmcnt(6)
	v_fmac_f32_e32 v56, v76, v96
	v_fmac_f32_e32 v56, v77, v97
	v_fmac_f32_e32 v56, v78, v98
	v_fmac_f32_e32 v56, v79, v99
	v_fmac_f32_e32 v56, v80, v100
	v_fmac_f32_e32 v56, v81, v101
	v_fmac_f32_e32 v56, v82, v102
	v_fmac_f32_e32 v56, v83, v103
	ds_read_b128 v[96:99], v95 offset:32768
	ds_read_b128 v[100:103], v95 offset:32784
	s_waitcnt lgkmcnt(6)
	v_fmac_f32_e32 v57, v76, v104
	v_fmac_f32_e32 v57, v77, v105
	v_fmac_f32_e32 v57, v78, v106
	v_fmac_f32_e32 v57, v79, v107
	v_fmac_f32_e32 v57, v80, v108
	v_fmac_f32_e32 v57, v81, v109
	v_fmac_f32_e32 v57, v82, v110
	v_fmac_f32_e32 v57, v83, v111
	ds_read_b128 v[104:107], v95 offset:36864
	ds_read_b128 v[108:111], v95 offset:36880
	s_waitcnt lgkmcnt(6)
	v_fmac_f32_e32 v50, v76, v112
	v_fmac_f32_e32 v50, v77, v113
	v_fmac_f32_e32 v50, v78, v114
	v_fmac_f32_e32 v50, v79, v115
	v_fmac_f32_e32 v50, v80, v116
	v_fmac_f32_e32 v50, v81, v117
	v_fmac_f32_e32 v50, v82, v118
	v_fmac_f32_e32 v50, v83, v119
	ds_read_b128 v[112:115], v95 offset:40960
	ds_read_b128 v[116:119], v95 offset:40976
	s_waitcnt lgkmcnt(6)
	v_fmac_f32_e32 v51, v76, v120
	v_fmac_f32_e32 v51, v77, v121
	v_fmac_f32_e32 v51, v78, v122
	v_fmac_f32_e32 v51, v79, v123
	v_fmac_f32_e32 v51, v80, v124
	v_fmac_f32_e32 v51, v81, v125
	v_fmac_f32_e32 v51, v82, v126
	v_fmac_f32_e32 v51, v83, v127
	ds_read_b128 v[120:123], v95 offset:45056
	ds_read_b128 v[124:127], v95 offset:45072
	s_waitcnt lgkmcnt(6)
	v_fmac_f32_e32 v48, v76, v96
	v_fmac_f32_e32 v48, v77, v97
	v_fmac_f32_e32 v48, v78, v98
	v_fmac_f32_e32 v48, v79, v99
	v_fmac_f32_e32 v48, v80, v100
	v_fmac_f32_e32 v48, v81, v101
	v_fmac_f32_e32 v48, v82, v102
	v_fmac_f32_e32 v48, v83, v103
	ds_read_b128 v[96:99], v95 offset:49152
	ds_read_b128 v[100:103], v95 offset:49168
	s_waitcnt lgkmcnt(6)
	v_fmac_f32_e32 v49, v76, v104
	v_fmac_f32_e32 v49, v77, v105
	v_fmac_f32_e32 v49, v78, v106
	v_fmac_f32_e32 v49, v79, v107
	v_fmac_f32_e32 v49, v80, v108
	v_fmac_f32_e32 v49, v81, v109
	v_fmac_f32_e32 v49, v82, v110
	v_fmac_f32_e32 v49, v83, v111
	ds_read_b128 v[104:107], v95 offset:53248
	ds_read_b128 v[108:111], v95 offset:53264
	s_waitcnt lgkmcnt(6)
	v_fmac_f32_e32 v46, v76, v112
	v_fmac_f32_e32 v46, v77, v113
	v_fmac_f32_e32 v46, v78, v114
	v_fmac_f32_e32 v46, v79, v115
	v_fmac_f32_e32 v46, v80, v116
	v_fmac_f32_e32 v46, v81, v117
	v_fmac_f32_e32 v46, v82, v118
	v_fmac_f32_e32 v46, v83, v119
	ds_read_b128 v[112:115], v95 offset:57344
	ds_read_b128 v[116:119], v95 offset:57360
	s_waitcnt lgkmcnt(6)
	v_fmac_f32_e32 v47, v76, v120
	v_fmac_f32_e32 v47, v77, v121
	v_fmac_f32_e32 v47, v78, v122
	v_fmac_f32_e32 v47, v79, v123
	v_fmac_f32_e32 v47, v80, v124
	v_fmac_f32_e32 v47, v81, v125
	v_fmac_f32_e32 v47, v82, v126
	v_fmac_f32_e32 v47, v83, v127
	ds_read_b128 v[120:123], v95 offset:61440
	ds_read_b128 v[124:127], v95 offset:61456
	s_waitcnt lgkmcnt(6)
; #define LAS __attribute__((address_space(3)))
; __device__ __forceinline__ void p0_phase(LAS unsigned char* lds, const float* c, const float* w_ada, const float* b_ada, const float* w_in, const float* w_out,
;                                          float* mod, bf16* win_t, bf16* wout_t, int tid, int wid, int lane) {
;     ...
; #pragma unroll 2
;         for (int k = 0; k < 128; k += 4) {
;             const float w0 = wp[(size_t)k * 3072], w1 = wp[(size_t)(k + 1) * 3072], w2 = wp[(size_t)(k + 2) * 3072], w3 = wp[(size_t)(k + 3) * 3072];
; #pragma unroll
;             for (int b = 0; b < 32; ++b) { const f32x4 cv = *(const LAS f32x4*)(cs + b * 1024 + kbase + k); acc[b] += cv[0] * w0 + cv[1] * w1 + cv[2] * w2 + cv[3] * w3; }
;         }
	v_fmac_f32_e32 v44, v76, v96
	v_fmac_f32_e32 v44, v77, v97
	v_fmac_f32_e32 v44, v78, v98
	v_fmac_f32_e32 v44, v79, v99
	v_fmac_f32_e32 v44, v80, v100
	v_fmac_f32_e32 v44, v81, v101
	v_fmac_f32_e32 v44, v82, v102
	v_fmac_f32_e32 v44, v83, v103
	s_waitcnt lgkmcnt(4)
	v_fmac_f32_e32 v45, v76, v104
	v_fmac_f32_e32 v45, v77, v105
	v_fmac_f32_e32 v45, v78, v106
	v_fmac_f32_e32 v45, v79, v107
	v_fmac_f32_e32 v45, v80, v108
	v_fmac_f32_e32 v45, v81, v109
	v_fmac_f32_e32 v45, v82, v110
	v_fmac_f32_e32 v45, v83, v111
	s_waitcnt lgkmcnt(2)
	v_fmac_f32_e32 v34, v76, v112
	v_fmac_f32_e32 v34, v77, v113
	v_fmac_f32_e32 v34, v78, v114
	v_fmac_f32_e32 v34, v79, v115
	v_fmac_f32_e32 v34, v80, v116
	v_fmac_f32_e32 v34, v81, v117
	v_fmac_f32_e32 v34, v82, v118
	v_fmac_f32_e32 v34, v83, v119
	s_waitcnt lgkmcnt(0)
	v_fmac_f32_e32 v35, v76, v120
	v_fmac_f32_e32 v35, v77, v121
	v_fmac_f32_e32 v35, v78, v122
	v_fmac_f32_e32 v35, v79, v123
	v_fmac_f32_e32 v35, v80, v124
	v_fmac_f32_e32 v35, v81, v125
	v_fmac_f32_e32 v35, v82, v126
	v_fmac_f32_e32 v35, v83, v127
	s_cmp_eq_u32 s52, 1
	s_cselect_b32 s50, 0xfffe8000, 0
	s_cselect_b32 s51, -1, 0
	v_lshl_add_u64 v[16:17], v[16:17], 0, s[50:51]
	v_add_co_u32_e32 v92, vcc, s24, v16
	s_nop 1
	v_addc_co_u32_e32 v93, vcc, -1, v17, vcc
	global_load_dword v76, v[92:93], off
	v_lshl_add_u64 v[92:93], v[92:93], 0, s[48:49]
	global_load_dword v77, v[92:93], off
	v_lshl_add_u64 v[92:93], v[92:93], 0, s[48:49]
	global_load_dword v78, v[92:93], off
	v_lshl_add_u64 v[92:93], v[92:93], 0, s[48:49]
	global_load_dword v79, v[92:93], off
	v_lshl_add_u64 v[92:93], v[92:93], 0, s[48:49]
	global_load_dword v80, v[92:93], off
	v_lshl_add_u64 v[92:93], v[92:93], 0, s[48:49]
	global_load_dword v81, v[92:93], off
	v_lshl_add_u64 v[92:93], v[92:93], 0, s[48:49]
	global_load_dword v82, v[92:93], off
	v_lshl_add_u64 v[92:93], v[92:93], 0, s[48:49]
	global_load_dword v83, v[92:93], off
	v_lshl_add_u64 v[16:17], v[16:17], 0, s[14:15]
	s_waitcnt vmcnt(8)
	ds_read_b128 v[96:99], v94 offset:32
	ds_read_b128 v[100:103], v94 offset:48
	ds_read_b128 v[104:107], v94 offset:4128
	ds_read_b128 v[108:111], v94 offset:4144
	ds_read_b128 v[112:115], v94 offset:8224
	ds_read_b128 v[116:119], v94 offset:8240
	ds_read_b128 v[120:123], v94 offset:12320
	ds_read_b128 v[124:127], v94 offset:12336
	s_waitcnt lgkmcnt(6)
	v_fmac_f32_e32 v18, v84, v96
	v_fmac_f32_e32 v18, v85, v97
	v_fmac_f32_e32 v18, v86, v98
	v_fmac_f32_e32 v18, v87, v99
	v_fmac_f32_e32 v18, v88, v100
	v_fmac_f32_e32 v18, v89, v101
	v_fmac_f32_e32 v18, v90, v102
	v_fmac_f32_e32 v18, v91, v103
	ds_read_b128 v[96:99], v94 offset:16416
	ds_read_b128 v[100:103], v94 offset:16432
	s_waitcnt lgkmcnt(6)
	v_fmac_f32_e32 v19, v84, v104
	v_fmac_f32_e32 v19, v85, v105
	v_fmac_f32_e32 v19, v86, v106
	v_fmac_f32_e32 v19, v87, v107
	v_fmac_f32_e32 v19, v88, v108
	v_fmac_f32_e32 v19, v89, v109
	v_fmac_f32_e32 v19, v90, v110
	v_fmac_f32_e32 v19, v91, v111
	ds_read_b128 v[104:107], v94 offset:20512
	ds_read_b128 v[108:111], v94 offset:20528
	s_waitcnt lgkmcnt(6)
	v_fmac_f32_e32 v20, v84, v112
	v_fmac_f32_e32 v20, v85, v113
	v_fmac_f32_e32 v20, v86, v114
	v_fmac_f32_e32 v20, v87, v115
	v_fmac_f32_e32 v20, v88, v116
	v_fmac_f32_e32 v20, v89, v117
	v_fmac_f32_e32 v20, v90, v118
	v_fmac_f32_e32 v20, v91, v119
	ds_read_b128 v[112:115], v94 offset:24608
	ds_read_b128 v[116:119], v94 offset:24624
	s_waitcnt lgkmcnt(6)
	v_fmac_f32_e32 v21, v84, v120
	v_fmac_f32_e32 v21, v85, v121
	v_fmac_f32_e32 v21, v86, v122
	v_fmac_f32_e32 v21, v87, v123
	v_fmac_f32_e32 v21, v88, v124
	v_fmac_f32_e32 v21, v89, v125
	v_fmac_f32_e32 v21, v90, v126
	v_fmac_f32_e32 v21, v91, v127
	ds_read_b128 v[120:123], v94 offset:28704
	ds_read_b128 v[124:127], v94 offset:28720
	s_waitcnt lgkmcnt(6)
	v_fmac_f32_e32 v22, v84, v96
	v_fmac_f32_e32 v22, v85, v97
	v_fmac_f32_e32 v22, v86, v98
	v_fmac_f32_e32 v22, v87, v99
	v_fmac_f32_e32 v22, v88, v100
	v_fmac_f32_e32 v22, v89, v101
	v_fmac_f32_e32 v22, v90, v102
	v_fmac_f32_e32 v22, v91, v103
	ds_read_b128 v[96:99], v94 offset:32800
	ds_read_b128 v[100:103], v94 offset:32816
	s_waitcnt lgkmcnt(6)
	v_fmac_f32_e32 v23, v84, v104
	v_fmac_f32_e32 v23, v85, v105
	v_fmac_f32_e32 v23, v86, v106
	v_fmac_f32_e32 v23, v87, v107
	v_fmac_f32_e32 v23, v88, v108
	v_fmac_f32_e32 v23, v89, v109
	v_fmac_f32_e32 v23, v90, v110
	v_fmac_f32_e32 v23, v91, v111
	ds_read_b128 v[104:107], v94 offset:36896
	ds_read_b128 v[108:111], v94 offset:36912
	s_waitcnt lgkmcnt(6)
	v_fmac_f32_e32 v24, v84, v112
	v_fmac_f32_e32 v24, v85, v113
	v_fmac_f32_e32 v24, v86, v114
	v_fmac_f32_e32 v24, v87, v115
	v_fmac_f32_e32 v24, v88, v116
	v_fmac_f32_e32 v24, v89, v117
	v_fmac_f32_e32 v24, v90, v118
	v_fmac_f32_e32 v24, v91, v119
	ds_read_b128 v[112:115], v94 offset:40992
	ds_read_b128 v[116:119], v94 offset:41008
	s_waitcnt lgkmcnt(6)
	v_fmac_f32_e32 v25, v84, v120
	v_fmac_f32_e32 v25, v85, v121
	v_fmac_f32_e32 v25, v86, v122
	v_fmac_f32_e32 v25, v87, v123
	v_fmac_f32_e32 v25, v88, v124
	v_fmac_f32_e32 v25, v89, v125
	v_fmac_f32_e32 v25, v90, v126
	v_fmac_f32_e32 v25, v91, v127
	ds_read_b128 v[120:123], v94 offset:45088
	ds_read_b128 v[124:127], v94 offset:45104
	s_waitcnt lgkmcnt(6)
	v_fmac_f32_e32 v26, v84, v96
	v_fmac_f32_e32 v26, v85, v97
	v_fmac_f32_e32 v26, v86, v98
	v_fmac_f32_e32 v26, v87, v99
	v_fmac_f32_e32 v26, v88, v100
	v_fmac_f32_e32 v26, v89, v101
	v_fmac_f32_e32 v26, v90, v102
	v_fmac_f32_e32 v26, v91, v103
	ds_read_b128 v[96:99], v94 offset:49184
	ds_read_b128 v[100:103], v94 offset:49200
	s_waitcnt lgkmcnt(6)
; #define LAS __attribute__((address_space(3)))
; __device__ __forceinline__ void p0_phase(LAS unsigned char* lds, const float* c, const float* w_ada, const float* b_ada, const float* w_in, const float* w_out,
;                                          float* mod, bf16* win_t, bf16* wout_t, int tid, int wid, int lane) {
;     ...
; #pragma unroll 2
;         for (int k = 0; k < 128; k += 4) {
;             const float w0 = wp[(size_t)k * 3072], w1 = wp[(size_t)(k + 1) * 3072], w2 = wp[(size_t)(k + 2) * 3072], w3 = wp[(size_t)(k + 3) * 3072];
; #pragma unroll
;             for (int b = 0; b < 32; ++b) { const f32x4 cv = *(const LAS f32x4*)(cs + b * 1024 + kbase + k); acc[b] += cv[0] * w0 + cv[1] * w1 + cv[2] * w2 + cv[3] * w3; }
;         }
	v_fmac_f32_e32 v27, v84, v104
	v_fmac_f32_e32 v27, v85, v105
	v_fmac_f32_e32 v27, v86, v106
	v_fmac_f32_e32 v27, v87, v107
	v_fmac_f32_e32 v27, v88, v108
	v_fmac_f32_e32 v27, v89, v109
	v_fmac_f32_e32 v27, v90, v110
	v_fmac_f32_e32 v27, v91, v111
	ds_read_b128 v[104:107], v94 offset:53280
	ds_read_b128 v[108:111], v94 offset:53296
	s_waitcnt lgkmcnt(6)
	v_fmac_f32_e32 v28, v84, v112
	v_fmac_f32_e32 v28, v85, v113
	v_fmac_f32_e32 v28, v86, v114
	v_fmac_f32_e32 v28, v87, v115
	v_fmac_f32_e32 v28, v88, v116
	v_fmac_f32_e32 v28, v89, v117
	v_fmac_f32_e32 v28, v90, v118
	v_fmac_f32_e32 v28, v91, v119
	ds_read_b128 v[112:115], v94 offset:57376
	ds_read_b128 v[116:119], v94 offset:57392
	s_waitcnt lgkmcnt(6)
	v_fmac_f32_e32 v29, v84, v120
	v_fmac_f32_e32 v29, v85, v121
	v_fmac_f32_e32 v29, v86, v122
	v_fmac_f32_e32 v29, v87, v123
	v_fmac_f32_e32 v29, v88, v124
	v_fmac_f32_e32 v29, v89, v125
	v_fmac_f32_e32 v29, v90, v126
	v_fmac_f32_e32 v29, v91, v127
	ds_read_b128 v[120:123], v94 offset:61472
	ds_read_b128 v[124:127], v94 offset:61488
	s_waitcnt lgkmcnt(6)
	v_fmac_f32_e32 v30, v84, v96
	v_fmac_f32_e32 v30, v85, v97
	v_fmac_f32_e32 v30, v86, v98
	v_fmac_f32_e32 v30, v87, v99
	v_fmac_f32_e32 v30, v88, v100
	v_fmac_f32_e32 v30, v89, v101
	v_fmac_f32_e32 v30, v90, v102
	v_fmac_f32_e32 v30, v91, v103
	ds_read_b128 v[96:99], v95 offset:32
	ds_read_b128 v[100:103], v95 offset:48
	s_waitcnt lgkmcnt(6)
	v_fmac_f32_e32 v31, v84, v104
	v_fmac_f32_e32 v31, v85, v105
	v_fmac_f32_e32 v31, v86, v106
	v_fmac_f32_e32 v31, v87, v107
	v_fmac_f32_e32 v31, v88, v108
	v_fmac_f32_e32 v31, v89, v109
	v_fmac_f32_e32 v31, v90, v110
	v_fmac_f32_e32 v31, v91, v111
	ds_read_b128 v[104:107], v95 offset:4128
	ds_read_b128 v[108:111], v95 offset:4144
	s_waitcnt lgkmcnt(6)
	v_fmac_f32_e32 v32, v84, v112
	v_fmac_f32_e32 v32, v85, v113
	v_fmac_f32_e32 v32, v86, v114
	v_fmac_f32_e32 v32, v87, v115
	v_fmac_f32_e32 v32, v88, v116
	v_fmac_f32_e32 v32, v89, v117
	v_fmac_f32_e32 v32, v90, v118
	v_fmac_f32_e32 v32, v91, v119
	ds_read_b128 v[112:115], v95 offset:8224
	ds_read_b128 v[116:119], v95 offset:8240
	s_waitcnt lgkmcnt(6)
	v_fmac_f32_e32 v33, v84, v120
	v_fmac_f32_e32 v33, v85, v121
	v_fmac_f32_e32 v33, v86, v122
	v_fmac_f32_e32 v33, v87, v123
	v_fmac_f32_e32 v33, v88, v124
	v_fmac_f32_e32 v33, v89, v125
	v_fmac_f32_e32 v33, v90, v126
	v_fmac_f32_e32 v33, v91, v127
	ds_read_b128 v[120:123], v95 offset:12320
	ds_read_b128 v[124:127], v95 offset:12336
	s_waitcnt lgkmcnt(6)
	v_fmac_f32_e32 v52, v84, v96
	v_fmac_f32_e32 v52, v85, v97
	v_fmac_f32_e32 v52, v86, v98
	v_fmac_f32_e32 v52, v87, v99
	v_fmac_f32_e32 v52, v88, v100
	v_fmac_f32_e32 v52, v89, v101
	v_fmac_f32_e32 v52, v90, v102
	v_fmac_f32_e32 v52, v91, v103
	ds_read_b128 v[96:99], v95 offset:16416
	ds_read_b128 v[100:103], v95 offset:16432
	s_waitcnt lgkmcnt(6)
	v_fmac_f32_e32 v53, v84, v104
	v_fmac_f32_e32 v53, v85, v105
	v_fmac_f32_e32 v53, v86, v106
	v_fmac_f32_e32 v53, v87, v107
	v_fmac_f32_e32 v53, v88, v108
	v_fmac_f32_e32 v53, v89, v109
	v_fmac_f32_e32 v53, v90, v110
	v_fmac_f32_e32 v53, v91, v111
	ds_read_b128 v[104:107], v95 offset:20512
	ds_read_b128 v[108:111], v95 offset:20528
	s_waitcnt lgkmcnt(6)
	v_fmac_f32_e32 v54, v84, v112
	v_fmac_f32_e32 v54, v85, v113
	v_fmac_f32_e32 v54, v86, v114
	v_fmac_f32_e32 v54, v87, v115
	v_fmac_f32_e32 v54, v88, v116
	v_fmac_f32_e32 v54, v89, v117
	v_fmac_f32_e32 v54, v90, v118
	v_fmac_f32_e32 v54, v91, v119
	ds_read_b128 v[112:115], v95 offset:24608
	ds_read_b128 v[116:119], v95 offset:24624
	s_waitcnt lgkmcnt(6)
	v_fmac_f32_e32 v55, v84, v120
	v_fmac_f32_e32 v55, v85, v121
	v_fmac_f32_e32 v55, v86, v122
	v_fmac_f32_e32 v55, v87, v123
	v_fmac_f32_e32 v55, v88, v124
	v_fmac_f32_e32 v55, v89, v125
	v_fmac_f32_e32 v55, v90, v126
	v_fmac_f32_e32 v55, v91, v127
	ds_read_b128 v[120:123], v95 offset:28704
	ds_read_b128 v[124:127], v95 offset:28720
	s_waitcnt lgkmcnt(6)
	v_fmac_f32_e32 v56, v84, v96
	v_fmac_f32_e32 v56, v85, v97
	v_fmac_f32_e32 v56, v86, v98
	v_fmac_f32_e32 v56, v87, v99
	v_fmac_f32_e32 v56, v88, v100
	v_fmac_f32_e32 v56, v89, v101
	v_fmac_f32_e32 v56, v90, v102
	v_fmac_f32_e32 v56, v91, v103
	ds_read_b128 v[96:99], v95 offset:32800
	ds_read_b128 v[100:103], v95 offset:32816
	s_waitcnt lgkmcnt(6)
	v_fmac_f32_e32 v57, v84, v104
	v_fmac_f32_e32 v57, v85, v105
	v_fmac_f32_e32 v57, v86, v106
	v_fmac_f32_e32 v57, v87, v107
	v_fmac_f32_e32 v57, v88, v108
	v_fmac_f32_e32 v57, v89, v109
	v_fmac_f32_e32 v57, v90, v110
	v_fmac_f32_e32 v57, v91, v111
	ds_read_b128 v[104:107], v95 offset:36896
	ds_read_b128 v[108:111], v95 offset:36912
	s_waitcnt lgkmcnt(6)
	v_fmac_f32_e32 v50, v84, v112
	v_fmac_f32_e32 v50, v85, v113
	v_fmac_f32_e32 v50, v86, v114
	v_fmac_f32_e32 v50, v87, v115
	v_fmac_f32_e32 v50, v88, v116
	v_fmac_f32_e32 v50, v89, v117
	v_fmac_f32_e32 v50, v90, v118
	v_fmac_f32_e32 v50, v91, v119
	ds_read_b128 v[112:115], v95 offset:40992
	ds_read_b128 v[116:119], v95 offset:41008
	s_waitcnt lgkmcnt(6)
	v_fmac_f32_e32 v51, v84, v120
	v_fmac_f32_e32 v51, v85, v121
	v_fmac_f32_e32 v51, v86, v122
	v_fmac_f32_e32 v51, v87, v123
	v_fmac_f32_e32 v51, v88, v124
	v_fmac_f32_e32 v51, v89, v125
	v_fmac_f32_e32 v51, v90, v126
	v_fmac_f32_e32 v51, v91, v127
	ds_read_b128 v[120:123], v95 offset:45088
	ds_read_b128 v[124:127], v95 offset:45104
	s_waitcnt lgkmcnt(6)
	v_fmac_f32_e32 v48, v84, v96
	v_fmac_f32_e32 v48, v85, v97
	v_fmac_f32_e32 v48, v86, v98
	v_fmac_f32_e32 v48, v87, v99
	v_fmac_f32_e32 v48, v88, v100
	v_fmac_f32_e32 v48, v89, v101
	v_fmac_f32_e32 v48, v90, v102
	v_fmac_f32_e32 v48, v91, v103
	ds_read_b128 v[96:99], v95 offset:49184
	ds_read_b128 v[100:103], v95 offset:49200
	s_waitcnt lgkmcnt(6)
; #define LAS __attribute__((address_space(3)))
; __device__ __forceinline__ void p0_phase(LAS unsigned char* lds, const float* c, const float* w_ada, const float* b_ada, const float* w_in, const float* w_out,
;                                          float* mod, bf16* win_t, bf16* wout_t, int tid, int wid, int lane) {
;     ...
;         __syncthreads();
;         LAS float* part = (LAS float*)lds;
; #pragma unroll
;         for (int b = 0; b < 32; ++b) part[(wid * 32 + b) * 64 + lane] = acc[b];
;         __syncthreads();
;         {
;             const int nn = tid & 63, bg = tid >> 6;
; #pragma unroll
;             for (int bb = 0; bb < 4; ++bb) { const int b = bg * 4 + bb; float s = 0.f;
; #pragma unroll
;                 for (int w = 0; w < 8; ++w) s += part[(w * 32 + b) * 64 + nn];
;                 mod[((size_t)l * 32 + b) * 3072 + nb * 64 + nn] = s + b_ada[l * 3072 + nb * 64 + nn]; }
;         }
;     }
	v_fmac_f32_e32 v49, v84, v104
	v_fmac_f32_e32 v49, v85, v105
	v_fmac_f32_e32 v49, v86, v106
	v_fmac_f32_e32 v49, v87, v107
	v_fmac_f32_e32 v49, v88, v108
	v_fmac_f32_e32 v49, v89, v109
	v_fmac_f32_e32 v49, v90, v110
	v_fmac_f32_e32 v49, v91, v111
	ds_read_b128 v[104:107], v95 offset:53280
	ds_read_b128 v[108:111], v95 offset:53296
	s_waitcnt lgkmcnt(6)
	v_fmac_f32_e32 v46, v84, v112
	v_fmac_f32_e32 v46, v85, v113
	v_fmac_f32_e32 v46, v86, v114
	v_fmac_f32_e32 v46, v87, v115
	v_fmac_f32_e32 v46, v88, v116
	v_fmac_f32_e32 v46, v89, v117
	v_fmac_f32_e32 v46, v90, v118
	v_fmac_f32_e32 v46, v91, v119
	ds_read_b128 v[112:115], v95 offset:57376
	ds_read_b128 v[116:119], v95 offset:57392
	s_waitcnt lgkmcnt(6)
	v_fmac_f32_e32 v47, v84, v120
	v_fmac_f32_e32 v47, v85, v121
	v_fmac_f32_e32 v47, v86, v122
	v_fmac_f32_e32 v47, v87, v123
	v_fmac_f32_e32 v47, v88, v124
	v_fmac_f32_e32 v47, v89, v125
	v_fmac_f32_e32 v47, v90, v126
	v_fmac_f32_e32 v47, v91, v127
	ds_read_b128 v[120:123], v95 offset:61472
	ds_read_b128 v[124:127], v95 offset:61488
	s_waitcnt lgkmcnt(6)
	v_fmac_f32_e32 v44, v84, v96
	v_fmac_f32_e32 v44, v85, v97
	v_fmac_f32_e32 v44, v86, v98
	v_fmac_f32_e32 v44, v87, v99
	v_fmac_f32_e32 v44, v88, v100
	v_fmac_f32_e32 v44, v89, v101
	v_fmac_f32_e32 v44, v90, v102
	v_fmac_f32_e32 v44, v91, v103
	s_waitcnt lgkmcnt(4)
	v_fmac_f32_e32 v45, v84, v104
	v_fmac_f32_e32 v45, v85, v105
	v_fmac_f32_e32 v45, v86, v106
	v_fmac_f32_e32 v45, v87, v107
	v_fmac_f32_e32 v45, v88, v108
	v_fmac_f32_e32 v45, v89, v109
	v_fmac_f32_e32 v45, v90, v110
	v_fmac_f32_e32 v45, v91, v111
	s_waitcnt lgkmcnt(2)
	v_fmac_f32_e32 v34, v84, v112
	v_fmac_f32_e32 v34, v85, v113
	v_fmac_f32_e32 v34, v86, v114
	v_fmac_f32_e32 v34, v87, v115
	v_fmac_f32_e32 v34, v88, v116
	v_fmac_f32_e32 v34, v89, v117
	v_fmac_f32_e32 v34, v90, v118
	v_fmac_f32_e32 v34, v91, v119
	s_waitcnt lgkmcnt(0)
	v_fmac_f32_e32 v35, v84, v120
	v_fmac_f32_e32 v35, v85, v121
	v_fmac_f32_e32 v35, v86, v122
	v_fmac_f32_e32 v35, v87, v123
	v_fmac_f32_e32 v35, v88, v124
	v_fmac_f32_e32 v35, v89, v125
	v_fmac_f32_e32 v35, v90, v126
	v_fmac_f32_e32 v35, v91, v127
	s_add_i32 s35, s35, 64
	s_add_i32 s52, s52, -1
	s_cmp_eq_u32 s52, 0
	s_cbranch_scc0 .LBB0_21
	s_waitcnt vmcnt(0)
	s_mul_i32 s34, s16, 48
	s_sub_i32 s34, s31, s34
	s_lshl_b32 s34, s34, 6
	v_add_u32_e32 v0, s19, v39
	s_add_i32 s33, s33, s34
	s_barrier
	ds_write2st64_b32 v0, v18, v19 offset1:1
	ds_write2st64_b32 v0, v20, v21 offset0:2 offset1:3
	ds_write2st64_b32 v0, v22, v23 offset0:4 offset1:5
	ds_write2st64_b32 v0, v24, v25 offset0:6 offset1:7
	ds_write2st64_b32 v0, v26, v27 offset0:8 offset1:9
	ds_write2st64_b32 v0, v28, v29 offset0:10 offset1:11
	ds_write2st64_b32 v0, v30, v31 offset0:12 offset1:13
	ds_write2st64_b32 v0, v32, v33 offset0:14 offset1:15
	ds_write2st64_b32 v0, v52, v53 offset0:16 offset1:17
	ds_write2st64_b32 v0, v54, v55 offset0:18 offset1:19
	ds_write2st64_b32 v0, v56, v57 offset0:20 offset1:21
	ds_write2st64_b32 v0, v50, v51 offset0:22 offset1:23
	ds_write2st64_b32 v0, v48, v49 offset0:24 offset1:25
	ds_write2st64_b32 v0, v46, v47 offset0:26 offset1:27
	ds_write2st64_b32 v0, v44, v45 offset0:28 offset1:29
	ds_write2st64_b32 v0, v34, v35 offset0:30 offset1:31
	v_or_b32_e32 v0, s33, v203
	v_ashrrev_i32_e32 v1, 31, v0
	v_lshl_add_u64 v[0:1], v[0:1], 2, s[4:5]
	s_waitcnt lgkmcnt(0)
	s_barrier
	global_load_dword v28, v[0:1], off
	ds_read2st64_b32 v[2:3], v59 offset1:32
	ds_read2st64_b32 v[16:17], v59 offset0:64 offset1:96
	ds_read2st64_b32 v[18:19], v59 offset0:128 offset1:160
	ds_read2st64_b32 v[20:21], v59 offset0:192 offset1:224
	s_lshl_b64 s[16:17], s[16:17], 5
	s_waitcnt lgkmcnt(3)
	v_add_f32_e32 v2, 0, v2
	v_add_f32_e32 v2, v2, v3
	s_waitcnt lgkmcnt(2)
	v_add_f32_e32 v2, v2, v16
	v_add_f32_e32 v2, v2, v17
	s_waitcnt lgkmcnt(1)
	v_add_f32_e32 v2, v2, v18
	s_ashr_i32 s35, s34, 31
	v_add_f32_e32 v2, v2, v19
	v_lshl_add_u64 v[22:23], s[16:17], 0, v[6:7]
	v_lshl_add_u64 v[24:25], s[34:35], 2, v[8:9]
	s_waitcnt lgkmcnt(0)
	v_add_f32_e32 v2, v2, v20
	v_mad_u64_u32 v[26:27], s[34:35], v22, s3, v[24:25]
	v_add_f32_e32 v2, v2, v21
	v_mad_i32_i24 v27, v23, s3, v27
	v_lshl_add_u64 v[22:23], s[16:17], 0, v[4:5]
	s_add_i32 s31, s31, s20
	s_cmpk_gt_i32 s31, 0x5f
	s_waitcnt vmcnt(0)
	v_add_f32_e32 v2, v2, v28
	global_store_dword v[26:27], v2, off sc1
	global_load_dword v28, v[0:1], off
	ds_read2st64_b32 v[2:3], v60 offset1:32
	ds_read2st64_b32 v[16:17], v60 offset0:64 offset1:96
	ds_read2st64_b32 v[18:19], v60 offset0:128 offset1:160
	ds_read2st64_b32 v[20:21], v60 offset0:192 offset1:224
	v_mad_u64_u32 v[26:27], s[34:35], v22, s3, v[24:25]
	s_waitcnt lgkmcnt(3)
	v_add_f32_e32 v2, 0, v2
	v_add_f32_e32 v2, v2, v3
	s_waitcnt lgkmcnt(2)
	v_add_f32_e32 v2, v2, v16
	v_add_f32_e32 v2, v2, v17
	s_waitcnt lgkmcnt(1)
	v_add_f32_e32 v2, v2, v18
	v_add_f32_e32 v2, v2, v19
	s_waitcnt lgkmcnt(0)
	v_add_f32_e32 v2, v2, v20
	v_add_f32_e32 v2, v2, v21
	v_mad_i32_i24 v27, v23, s3, v27
	v_lshl_add_u64 v[22:23], s[16:17], 0, v[10:11]
	s_waitcnt vmcnt(0)
	v_add_f32_e32 v2, v2, v28
	global_store_dword v[26:27], v2, off sc1
	global_load_dword v28, v[0:1], off
	ds_read2st64_b32 v[2:3], v61 offset1:32
	ds_read2st64_b32 v[16:17], v61 offset0:64 offset1:96
	ds_read2st64_b32 v[18:19], v61 offset0:128 offset1:160
	ds_read2st64_b32 v[20:21], v61 offset0:192 offset1:224
	v_mad_u64_u32 v[26:27], s[34:35], v22, s3, v[24:25]
	s_waitcnt lgkmcnt(3)
	v_add_f32_e32 v2, 0, v2
	v_add_f32_e32 v2, v2, v3
	s_waitcnt lgkmcnt(2)
	v_add_f32_e32 v2, v2, v16
	v_add_f32_e32 v2, v2, v17
	s_waitcnt lgkmcnt(1)
	v_add_f32_e32 v2, v2, v18
	v_add_f32_e32 v2, v2, v19
	s_waitcnt lgkmcnt(0)
	v_add_f32_e32 v2, v2, v20
	v_add_f32_e32 v2, v2, v21
	v_mad_i32_i24 v27, v23, s3, v27
	v_lshl_add_u64 v[20:21], s[16:17], 0, v[12:13]
	v_mad_u64_u32 v[22:23], s[16:17], v20, s3, v[24:25]
	v_mad_i32_i24 v23, v21, s3, v23
	s_waitcnt vmcnt(0)
	v_add_f32_e32 v2, v2, v28
	global_store_dword v[26:27], v2, off sc1
	global_load_dword v26, v[0:1], off
	ds_read2st64_b32 v[0:1], v62 offset1:32
	ds_read2st64_b32 v[2:3], v62 offset0:64 offset1:96
	ds_read2st64_b32 v[16:17], v62 offset0:128 offset1:160
	ds_read2st64_b32 v[18:19], v62 offset0:192 offset1:224
	s_waitcnt lgkmcnt(3)
	v_add_f32_e32 v0, 0, v0
	v_add_f32_e32 v0, v0, v1
	s_waitcnt lgkmcnt(2)
	v_add_f32_e32 v0, v0, v2
	v_add_f32_e32 v0, v0, v3
	s_waitcnt lgkmcnt(1)
	v_add_f32_e32 v0, v0, v16
	v_add_f32_e32 v0, v0, v17
	s_waitcnt lgkmcnt(0)
	v_add_f32_e32 v0, v0, v18
	v_add_f32_e32 v0, v0, v19
	s_waitcnt vmcnt(0)
	v_add_f32_e32 v0, v0, v26
	global_store_dword v[22:23], v0, off sc1
	s_cbranch_scc0 .LBB0_18

; __device__ __forceinline__ void fast_grid_barrier(unsigned* base, int seam, int tid) {
;     asm volatile("s_waitcnt vmcnt(0)" ::: "memory");
;     __syncthreads();
;     if (tid == 0) {
;         unsigned* cnt = base + seam * 128;
;         unsigned* flg = cnt + 64;
;         __builtin_amdgcn_fence(__ATOMIC_RELEASE, "agent");
;         asm volatile("s_waitcnt vmcnt(0)" ::: "memory");
;         const unsigned old = __hip_atomic_fetch_add(cnt, 1u, __ATOMIC_RELAXED, __HIP_MEMORY_SCOPE_AGENT);
;         if (old == gridDim.x - 1) __hip_atomic_store(flg, 1u, __ATOMIC_RELAXED, __HIP_MEMORY_SCOPE_AGENT);
;         else { unsigned sp = 0; while (__hip_atomic_load(flg, __ATOMIC_RELAXED, __HIP_MEMORY_SCOPE_AGENT) == 0u) { __builtin_amdgcn_s_sleep(2); if (++sp > (1u << 22)) break; } }
.LBB0_60:
.LBB0_61:
	s_cmp_lt_i32 s47, 2
	s_cbranch_scc1 .LBB0_78
	s_waitcnt vmcnt(0)
	v_cmp_eq_u32_e32 vcc, 0, v202
	s_barrier
	s_and_saveexec_b64 s[0:1], vcc
	s_cbranch_execz .LBB0_77
	s_mov_b64 s[4:5], exec
	s_nop 0
	s_waitcnt vmcnt(0)
	s_waitcnt vmcnt(0)
	v_mbcnt_lo_u32_b32 v0, s4, 0
	v_mbcnt_hi_u32_b32 v0, s5, v0
	v_cmp_eq_u32_e32 vcc, 0, v0
	s_and_saveexec_b64 s[6:7], vcc
	s_cbranch_execz .LBB0_65
	s_bcnt1_i32_b64 s3, s[4:5]
	v_mov_b32_e32 v1, 0
	v_mov_b32_e32 v2, s3
	global_atomic_add v1, v1, v2, s[44:45] offset:1024 sc0
